# w_in GEMM epilogue: hand-written fast path for the tiles whose columns are both u segments (scale, pack, A2 scatter store, hoisted row-statistic loads); other tile columns keep the compiled path
# speedup vs baseline: 1.0078x; 1.0020x over previous
.LBB0_295:
	s_cmp_gt_i32 s4, 1
	s_cbranch_scc1 .Lwin_slow
	v_and_b32_e32 v177, 15, v192
	v_bfe_u32 v162, v192, 6, 2
	v_bfe_u32 v163, v192, 4, 2
	v_ashrrev_i32_e32 v80, 2, v192
	v_and_b32_e32 v80, 0xffffffc0, v80
	v_lshl_or_b32 v164, s52, 8, v177
	v_add_u32_e32 v164, v164, v80
	v_ashrrev_i32_e32 v165, 31, v164
	v_lshl_add_u64 v[166:167], v[164:165], 2, s[90:91]
	s_mov_b64 vcc, 0x20000
	s_nop 0
	v_lshl_add_u64 v[166:167], v[166:167], 0, vcc
	global_load_dword v214, v[166:167], off
	global_load_dword v215, v[166:167], off offset:64
	global_load_dword v216, v[166:167], off offset:128
	global_load_dword v217, v[166:167], off offset:192
	global_load_dword v218, v[166:167], off offset:512
	global_load_dword v219, v[166:167], off offset:576
	global_load_dword v220, v[166:167], off offset:640
	global_load_dword v221, v[166:167], off offset:704
	s_lshl_b32 s43, s4, 8
	v_lshlrev_b32_e32 v168, 5, v162
	v_lshlrev_b32_e32 v169, 3, v163
	v_or3_b32 v168, v168, s43, v169
	v_ashrrev_i32_e32 v170, 4, v168
	v_lshlrev_b32_e32 v170, 10, v170
	v_ashrrev_i32_e32 v171, 5, v164
	v_add_u32_e32 v170, v170, v171
	v_mul_u32_u24_e32 v170, 0x500, v170
	v_lshlrev_b32_e32 v171, 5, v177
	v_and_b32_e32 v169, 8, v169
	v_lshlrev_b32_e32 v169, 1, v169
	v_add3_u32 v170, v170, v171, v169
	v_mov_b32_e32 v171, v81
	v_lshl_add_u64 v[170:171], v[170:171], 0, s[62:63]
	s_mov_b64 vcc, 0x1400
	s_nop 0
	v_lshl_add_u64 v[172:173], v[170:171], 0, vcc
	s_mov_b64 vcc, 0xa00000
	s_nop 0
	v_lshl_add_u64 v[174:175], v[170:171], 0, vcc
	v_lshl_add_u64 v[178:179], v[172:173], 0, vcc
	s_waitcnt vmcnt(7)
	v_fmamk_f32 v180, v214, 0x3a800000, v194
	v_rsq_f32_e32 v180, v180
	s_nop 0
	v_pk_mul_f32 v[126:127], v[126:127], v[180:181] op_sel_hi:[1,0]
	v_pk_mul_f32 v[128:129], v[128:129], v[180:181] op_sel_hi:[1,0]
	v_pk_mul_f32 v[122:123], v[122:123], v[180:181] op_sel_hi:[1,0]
	v_pk_mul_f32 v[124:125], v[124:125], v[180:181] op_sel_hi:[1,0]
	v_cvt_pk_bf16_f32 v126, v126, v127
	v_cvt_pk_bf16_f32 v127, v128, v129
	v_cvt_pk_bf16_f32 v128, v122, v123
	v_cvt_pk_bf16_f32 v129, v124, v125
	global_store_dwordx4 v[170:171], v[126:129], off
	v_pk_mul_f32 v[118:119], v[118:119], v[180:181] op_sel_hi:[1,0]
	v_pk_mul_f32 v[120:121], v[120:121], v[180:181] op_sel_hi:[1,0]
	v_pk_mul_f32 v[114:115], v[114:115], v[180:181] op_sel_hi:[1,0]
	v_pk_mul_f32 v[116:117], v[116:117], v[180:181] op_sel_hi:[1,0]
	v_cvt_pk_bf16_f32 v118, v118, v119
	v_cvt_pk_bf16_f32 v119, v120, v121
	v_cvt_pk_bf16_f32 v120, v114, v115
	v_cvt_pk_bf16_f32 v121, v116, v117
	global_store_dwordx4 v[174:175], v[118:121], off
	s_waitcnt vmcnt(8)
	v_fmamk_f32 v180, v215, 0x3a800000, v194
	v_rsq_f32_e32 v180, v180
	s_nop 0
	v_pk_mul_f32 v[110:111], v[110:111], v[180:181] op_sel_hi:[1,0]
	v_pk_mul_f32 v[112:113], v[112:113], v[180:181] op_sel_hi:[1,0]
	v_pk_mul_f32 v[106:107], v[106:107], v[180:181] op_sel_hi:[1,0]
	v_pk_mul_f32 v[108:109], v[108:109], v[180:181] op_sel_hi:[1,0]
	v_cvt_pk_bf16_f32 v110, v110, v111
	v_cvt_pk_bf16_f32 v111, v112, v113
	v_cvt_pk_bf16_f32 v112, v106, v107
	v_cvt_pk_bf16_f32 v113, v108, v109
	global_store_dwordx4 v[170:171], v[110:113], off offset:512
	v_pk_mul_f32 v[102:103], v[102:103], v[180:181] op_sel_hi:[1,0]
	v_pk_mul_f32 v[104:105], v[104:105], v[180:181] op_sel_hi:[1,0]
	v_pk_mul_f32 v[98:99], v[98:99], v[180:181] op_sel_hi:[1,0]
	v_pk_mul_f32 v[100:101], v[100:101], v[180:181] op_sel_hi:[1,0]
	v_cvt_pk_bf16_f32 v102, v102, v103
	v_cvt_pk_bf16_f32 v103, v104, v105
	v_cvt_pk_bf16_f32 v104, v98, v99
	v_cvt_pk_bf16_f32 v105, v100, v101
	global_store_dwordx4 v[174:175], v[102:105], off offset:512
	s_waitcnt vmcnt(9)
	v_fmamk_f32 v180, v216, 0x3a800000, v194
	v_rsq_f32_e32 v180, v180
	s_nop 0
	v_pk_mul_f32 v[94:95], v[94:95], v[180:181] op_sel_hi:[1,0]
	v_pk_mul_f32 v[96:97], v[96:97], v[180:181] op_sel_hi:[1,0]
	v_pk_mul_f32 v[90:91], v[90:91], v[180:181] op_sel_hi:[1,0]
	v_pk_mul_f32 v[92:93], v[92:93], v[180:181] op_sel_hi:[1,0]
	v_cvt_pk_bf16_f32 v94, v94, v95
	v_cvt_pk_bf16_f32 v95, v96, v97
	v_cvt_pk_bf16_f32 v96, v90, v91
	v_cvt_pk_bf16_f32 v97, v92, v93
	global_store_dwordx4 v[170:171], v[94:97], off offset:1280
	v_pk_mul_f32 v[86:87], v[86:87], v[180:181] op_sel_hi:[1,0]
	v_pk_mul_f32 v[88:89], v[88:89], v[180:181] op_sel_hi:[1,0]
	v_pk_mul_f32 v[82:83], v[82:83], v[180:181] op_sel_hi:[1,0]
	v_pk_mul_f32 v[84:85], v[84:85], v[180:181] op_sel_hi:[1,0]
	v_cvt_pk_bf16_f32 v86, v86, v87
	v_cvt_pk_bf16_f32 v87, v88, v89
	v_cvt_pk_bf16_f32 v88, v82, v83
	v_cvt_pk_bf16_f32 v89, v84, v85
	global_store_dwordx4 v[174:175], v[86:89], off offset:1280
	s_waitcnt vmcnt(10)
	v_fmamk_f32 v180, v217, 0x3a800000, v194
	v_rsq_f32_e32 v180, v180
	s_nop 0
	v_pk_mul_f32 v[76:77], v[76:77], v[180:181] op_sel_hi:[1,0]
	v_pk_mul_f32 v[78:79], v[78:79], v[180:181] op_sel_hi:[1,0]
	v_pk_mul_f32 v[72:73], v[72:73], v[180:181] op_sel_hi:[1,0]
	v_pk_mul_f32 v[74:75], v[74:75], v[180:181] op_sel_hi:[1,0]
	v_cvt_pk_bf16_f32 v76, v76, v77
	v_cvt_pk_bf16_f32 v77, v78, v79
	v_cvt_pk_bf16_f32 v78, v72, v73
	v_cvt_pk_bf16_f32 v79, v74, v75
	global_store_dwordx4 v[170:171], v[76:79], off offset:1792
	v_pk_mul_f32 v[68:69], v[68:69], v[180:181] op_sel_hi:[1,0]
	v_pk_mul_f32 v[70:71], v[70:71], v[180:181] op_sel_hi:[1,0]
	v_pk_mul_f32 v[64:65], v[64:65], v[180:181] op_sel_hi:[1,0]
	v_pk_mul_f32 v[66:67], v[66:67], v[180:181] op_sel_hi:[1,0]
	v_cvt_pk_bf16_f32 v68, v68, v69
	v_cvt_pk_bf16_f32 v69, v70, v71
	v_cvt_pk_bf16_f32 v70, v64, v65
	v_cvt_pk_bf16_f32 v71, v66, v67
	global_store_dwordx4 v[174:175], v[68:71], off offset:1792
	s_waitcnt vmcnt(11)
	v_fmamk_f32 v180, v218, 0x3a800000, v194
	v_rsq_f32_e32 v180, v180
	s_nop 0
	v_pk_mul_f32 v[60:61], v[60:61], v[180:181] op_sel_hi:[1,0]
	v_pk_mul_f32 v[62:63], v[62:63], v[180:181] op_sel_hi:[1,0]
	v_pk_mul_f32 v[56:57], v[56:57], v[180:181] op_sel_hi:[1,0]
	v_pk_mul_f32 v[58:59], v[58:59], v[180:181] op_sel_hi:[1,0]
	v_cvt_pk_bf16_f32 v60, v60, v61
	v_cvt_pk_bf16_f32 v61, v62, v63
	v_cvt_pk_bf16_f32 v62, v56, v57
	v_cvt_pk_bf16_f32 v63, v58, v59
	global_store_dwordx4 v[172:173], v[60:63], off
	v_pk_mul_f32 v[52:53], v[52:53], v[180:181] op_sel_hi:[1,0]
	v_pk_mul_f32 v[54:55], v[54:55], v[180:181] op_sel_hi:[1,0]
	v_pk_mul_f32 v[48:49], v[48:49], v[180:181] op_sel_hi:[1,0]
	v_pk_mul_f32 v[50:51], v[50:51], v[180:181] op_sel_hi:[1,0]
	v_cvt_pk_bf16_f32 v52, v52, v53
	v_cvt_pk_bf16_f32 v53, v54, v55
	v_cvt_pk_bf16_f32 v54, v48, v49
	v_cvt_pk_bf16_f32 v55, v50, v51
	global_store_dwordx4 v[178:179], v[52:55], off
	s_waitcnt vmcnt(12)
	v_fmamk_f32 v180, v219, 0x3a800000, v194
	v_rsq_f32_e32 v180, v180
	s_nop 0
	v_pk_mul_f32 v[44:45], v[44:45], v[180:181] op_sel_hi:[1,0]
	v_pk_mul_f32 v[46:47], v[46:47], v[180:181] op_sel_hi:[1,0]
	v_pk_mul_f32 v[40:41], v[40:41], v[180:181] op_sel_hi:[1,0]
	v_pk_mul_f32 v[42:43], v[42:43], v[180:181] op_sel_hi:[1,0]
	v_cvt_pk_bf16_f32 v44, v44, v45
	v_cvt_pk_bf16_f32 v45, v46, v47
	v_cvt_pk_bf16_f32 v46, v40, v41
	v_cvt_pk_bf16_f32 v47, v42, v43
	global_store_dwordx4 v[172:173], v[44:47], off offset:512
	v_pk_mul_f32 v[36:37], v[36:37], v[180:181] op_sel_hi:[1,0]
	v_pk_mul_f32 v[38:39], v[38:39], v[180:181] op_sel_hi:[1,0]
	v_pk_mul_f32 v[32:33], v[32:33], v[180:181] op_sel_hi:[1,0]
	v_pk_mul_f32 v[34:35], v[34:35], v[180:181] op_sel_hi:[1,0]
	v_cvt_pk_bf16_f32 v36, v36, v37
	v_cvt_pk_bf16_f32 v37, v38, v39
	v_cvt_pk_bf16_f32 v38, v32, v33
	v_cvt_pk_bf16_f32 v39, v34, v35
	global_store_dwordx4 v[178:179], v[36:39], off offset:512
	s_waitcnt vmcnt(13)
	v_fmamk_f32 v180, v220, 0x3a800000, v194
	v_rsq_f32_e32 v180, v180
	s_nop 0
	v_pk_mul_f32 v[28:29], v[28:29], v[180:181] op_sel_hi:[1,0]
	v_pk_mul_f32 v[30:31], v[30:31], v[180:181] op_sel_hi:[1,0]
	v_pk_mul_f32 v[24:25], v[24:25], v[180:181] op_sel_hi:[1,0]
	v_pk_mul_f32 v[26:27], v[26:27], v[180:181] op_sel_hi:[1,0]
	v_cvt_pk_bf16_f32 v28, v28, v29
	v_cvt_pk_bf16_f32 v29, v30, v31
	v_cvt_pk_bf16_f32 v30, v24, v25
	v_cvt_pk_bf16_f32 v31, v26, v27
	global_store_dwordx4 v[172:173], v[28:31], off offset:1280
	v_pk_mul_f32 v[20:21], v[20:21], v[180:181] op_sel_hi:[1,0]
	v_pk_mul_f32 v[22:23], v[22:23], v[180:181] op_sel_hi:[1,0]
	v_pk_mul_f32 v[16:17], v[16:17], v[180:181] op_sel_hi:[1,0]
	v_pk_mul_f32 v[18:19], v[18:19], v[180:181] op_sel_hi:[1,0]
	v_cvt_pk_bf16_f32 v20, v20, v21
	v_cvt_pk_bf16_f32 v21, v22, v23
	v_cvt_pk_bf16_f32 v22, v16, v17
	v_cvt_pk_bf16_f32 v23, v18, v19
	global_store_dwordx4 v[178:179], v[20:23], off offset:1280
	s_waitcnt vmcnt(14)
	v_fmamk_f32 v180, v221, 0x3a800000, v194
	v_rsq_f32_e32 v180, v180
	s_nop 0
	v_pk_mul_f32 v[12:13], v[12:13], v[180:181] op_sel_hi:[1,0]
	v_pk_mul_f32 v[14:15], v[14:15], v[180:181] op_sel_hi:[1,0]
	v_pk_mul_f32 v[8:9], v[8:9], v[180:181] op_sel_hi:[1,0]
	v_pk_mul_f32 v[10:11], v[10:11], v[180:181] op_sel_hi:[1,0]
	v_cvt_pk_bf16_f32 v12, v12, v13
	v_cvt_pk_bf16_f32 v13, v14, v15
	v_cvt_pk_bf16_f32 v14, v8, v9
	v_cvt_pk_bf16_f32 v15, v10, v11
	global_store_dwordx4 v[172:173], v[12:15], off offset:1792
	v_pk_mul_f32 v[4:5], v[4:5], v[180:181] op_sel_hi:[1,0]
	v_pk_mul_f32 v[6:7], v[6:7], v[180:181] op_sel_hi:[1,0]
	v_pk_mul_f32 v[0:1], v[0:1], v[180:181] op_sel_hi:[1,0]
	v_pk_mul_f32 v[2:3], v[2:3], v[180:181] op_sel_hi:[1,0]
	v_cvt_pk_bf16_f32 v4, v4, v5
	v_cvt_pk_bf16_f32 v5, v6, v7
	v_cvt_pk_bf16_f32 v6, v0, v1
	v_cvt_pk_bf16_f32 v7, v2, v3
	global_store_dwordx4 v[178:179], v[4:7], off offset:1792
	s_mov_b64 s[48:49], exec
	s_branch .LBB0_612
